# prompt attention: cvt_pk_bf16 for P pack and double-buffered V fragment LDS reads
# speedup vs baseline: 1.0746x; 1.0037x over previous
.LBB0_1014:
	s_min_u32 s5, s4, s3
	s_lshl_b32 s8, s5, 7
	v_lshl_add_u64 v[116:117], v[174:175], 0, s[8:9]
	s_mul_i32 s8, s5, 0x30000
	v_lshl_add_u64 v[112:113], v[172:173], 0, s[8:9]
	global_load_dwordx4 v[84:87], v[112:113], off offset:1024
	global_load_dwordx4 v[88:91], v[116:117], off
	ds_read_b128 v[152:155], v237 offset:35840
	ds_read_b128 v[156:159], v237 offset:35904
	v_add_co_u32_e32 v92, vcc, 0xc000, v112
	s_mov_b32 s7, s9
	s_nop 0
	v_addc_co_u32_e32 v93, vcc, 0, v113, vcc
	s_waitcnt lgkmcnt(1)
	v_mfma_f32_16x16x32_bf16 v[152:155], v[152:155], v[60:63], v[108:111]
	v_add_co_u32_e32 v96, vcc, 0x100000, v116
	ds_read_b128 v[160:163], v237 offset:40256
	s_waitcnt lgkmcnt(1)
	v_mfma_f32_16x16x32_bf16 v[152:155], v[156:159], v[64:67], v[152:155]
	ds_read_b128 v[156:159], v237 offset:40192
	v_addc_co_u32_e32 v97, vcc, 0, v117, vcc
	v_add_co_u32_e32 v100, vcc, 0x18000, v112
	global_load_dwordx4 v[92:95], v[92:93], off offset:1024
	s_waitcnt lgkmcnt(0)
	v_mfma_f32_16x16x32_bf16 v[156:159], v[156:159], v[60:63], v[108:111]
	ds_read_b128 v[164:167], v237 offset:44608
	s_nop 0
	v_exp_f32_e32 v199, v155
	v_exp_f32_e32 v191, v153
	v_mfma_f32_16x16x32_bf16 v[156:159], v[160:163], v[64:67], v[156:159]
	ds_read_b128 v[160:163], v237 offset:44544
	v_addc_co_u32_e32 v101, vcc, 0, v113, vcc
	s_waitcnt lgkmcnt(0)
	v_mfma_f32_16x16x32_bf16 v[160:163], v[160:163], v[60:63], v[108:111]
	s_nop 1
	s_nop 1
	v_exp_f32_e32 v197, v157
	v_exp_f32_e32 v189, v156
	v_exp_f32_e32 v195, v158
	v_mfma_f32_16x16x32_bf16 v[180:183], v[164:167], v[64:67], v[160:163]
	ds_read_b128 v[164:167], v237 offset:48960
	v_exp_f32_e32 v201, v159
	ds_read_b128 v[160:163], v237 offset:48896
	s_waitcnt lgkmcnt(0)
	v_mfma_f32_16x16x32_bf16 v[160:163], v[160:163], v[60:63], v[108:111]
	s_nop 1
	s_nop 0
	v_exp_f32_e32 v185, v183
	ds_read_b128 v[220:223], v237 offset:36032
	v_exp_f32_e32 v181, v181
	v_mfma_f32_16x16x32_bf16 v[210:213], v[164:167], v[64:67], v[160:163]
	v_exp_f32_e32 v167, v154
	v_exp_f32_e32 v165, v152
	s_nop 0
	v_exp_f32_e32 v161, v180
	s_nop 2
	s_nop 0
	v_exp_f32_e32 v179, v210
	v_exp_f32_e32 v187, v211
	v_exp_f32_e32 v183, v212
	v_exp_f32_e32 v193, v213
	ds_read_b128 v[210:213], v237 offset:35968
	s_waitcnt lgkmcnt(0)
	v_mfma_f32_16x16x32_bf16 v[210:213], v[210:213], v[68:71], v[108:111]
	ds_read_b128 v[224:227], v237 offset:40384
	ds_read_b128 v[240:243], v237 offset:44736
	v_mfma_f32_16x16x32_bf16 v[210:213], v[220:223], v[72:75], v[210:213]
	ds_read_b128 v[220:223], v237 offset:40320
	v_exp_f32_e32 v163, v182
	s_waitcnt lgkmcnt(0)
	v_mfma_f32_16x16x32_bf16 v[220:223], v[220:223], v[68:71], v[108:111]
	v_mfma_f32_16x16x32_bf16 v[220:223], v[224:227], v[72:75], v[220:223]
	ds_read_b128 v[224:227], v237 offset:44672
	v_cvt_pk_bf16_f32 v157, v167, v199
	s_waitcnt lgkmcnt(0)
	v_mfma_f32_16x16x32_bf16 v[224:227], v[224:227], v[68:71], v[108:111]
	v_mfma_f32_16x16x32_bf16 v[224:227], v[240:243], v[72:75], v[224:227]
	ds_read_b128 v[240:243], v237 offset:49024
	ds_read_b128 v[244:247], v237 offset:49088
	v_cvt_pk_bf16_f32 v156, v165, v191
	v_exp_f32_e32 v164, v210
	v_exp_f32_e32 v190, v211
	v_exp_f32_e32 v166, v212
	v_exp_f32_e32 v198, v213
	s_waitcnt lgkmcnt(1)
	v_mfma_f32_16x16x32_bf16 v[240:243], v[240:243], v[68:71], v[108:111]
	v_exp_f32_e32 v188, v220
	v_pk_add_f32 v[210:211], v[164:165], 0 op_sel_hi:[1,0]
	v_exp_f32_e32 v196, v221
	v_pk_add_f32 v[210:211], v[190:191], v[210:211]
	v_cvt_pk_bf16_f32 v159, v195, v201
	v_pk_add_f32 v[210:211], v[166:167], v[210:211]
	v_exp_f32_e32 v194, v222
	v_cvt_pk_bf16_f32 v158, v189, v197
	v_pk_add_f32 v[210:211], v[198:199], v[210:211]
	v_exp_f32_e32 v200, v223
	v_cvt_pk_bf16_f32 v155, v183, v193
	v_cvt_pk_bf16_f32 v152, v161, v181
	s_waitcnt lgkmcnt(0)
	v_mfma_f32_16x16x32_bf16 v[240:243], v[244:247], v[72:75], v[240:243]
	v_add_f32_e64 v210, v210, v188
	v_add_f32_e64 v211, v211, v189
	v_exp_f32_e32 v160, v224
	v_cvt_pk_bf16_f32 v154, v179, v187
	v_cvt_pk_bf16_f32 v153, v163, v185
	v_pk_add_f32 v[210:211], v[196:197], v[210:211]
	v_exp_f32_e32 v180, v225
	v_exp_f32_e32 v162, v226
	v_pk_add_f32 v[210:211], v[194:195], v[210:211]
	v_exp_f32_e32 v184, v227
	v_pk_add_f32 v[210:211], v[200:201], v[210:211]
	v_exp_f32_e32 v178, v240
	v_pk_add_f32 v[210:211], v[210:211], v[160:161]
	v_exp_f32_e32 v186, v241
	v_pk_add_f32 v[210:211], v[180:181], v[210:211]
	v_exp_f32_e32 v182, v242
	v_pk_add_f32 v[210:211], v[162:163], v[210:211]
	v_pk_add_f32 v[210:211], v[184:185], v[210:211]
	v_pk_add_f32 v[210:211], v[210:211], v[178:179]
	v_bfe_u32 v165, v166, 16, 1
	v_exp_f32_e32 v192, v243
	v_pk_add_f32 v[210:211], v[186:187], v[210:211]
	v_bfe_u32 v163, v198, 16, 1
	v_add3_u32 v165, v166, v165, s33
	v_pk_add_f32 v[210:211], v[182:183], v[210:211]
	v_add3_u32 v163, v198, v163, s33
	v_lshrrev_b32_e32 v165, 16, v165
	v_and_or_b32 v165, v163, s6, v165
	v_cvt_pk_bf16_f32 v166, v188, v196
	v_bfe_u32 v163, v184, 16, 1
	v_add3_u32 v183, v184, v163, s33
	v_bfe_u32 v163, v162, 16, 1
	v_bfe_u32 v181, v182, 16, 1
	v_bfe_u32 v185, v178, 16, 1
	v_cvt_pk_bf16_f32 v167, v194, v200
	v_cvt_pk_bf16_f32 v164, v164, v190
	v_bfe_u32 v161, v192, 16, 1
	v_bfe_u32 v179, v186, 16, 1
	v_add3_u32 v181, v182, v181, s33
	v_add3_u32 v162, v162, v163, s33
	v_add3_u32 v163, v178, v185, s33
	v_add3_u32 v161, v192, v161, s33
	v_add3_u32 v179, v186, v179, s33
	v_lshrrev_b32_e32 v162, 16, v162
	v_lshrrev_b32_e32 v178, 16, v181
	v_lshrrev_b32_e32 v181, 16, v163
	v_add_u32_e32 v182, 0xd000, v238
	v_and_or_b32 v163, v161, s6, v178
	v_and_or_b32 v161, v183, s6, v162
	v_and_or_b32 v162, v179, s6, v181
	v_cvt_pk_bf16_f32 v160, v160, v180
	ds_read2_b64 v[178:181], v182 offset1:4
	ds_read2_b64 v[216:219], v182 offset0:8 offset1:12
	s_waitcnt lgkmcnt(1)
	v_mfma_f32_16x16x32_bf16 v[76:79], v[178:181], v[156:159], v[76:79]
	v_add_co_u32_e32 v104, vcc, 0x200000, v116
	global_load_dwordx4 v[96:99], v[96:97], off
	v_mfma_f32_16x16x32_bf16 v[80:83], v[178:181], v[164:167], v[80:83]
	v_add_u32_e32 v182, 0xd800, v238
	v_addc_co_u32_e32 v105, vcc, 0, v117, vcc
	ds_read2_b64 v[178:181], v182 offset0:32 offset1:36
	s_waitcnt lgkmcnt(1)
	v_mfma_f32_16x16x32_bf16 v[76:79], v[216:219], v[152:155], v[76:79]
	v_add_co_u32_e32 v112, vcc, 0x24000, v112
	global_load_dwordx4 v[100:103], v[100:101], off offset:1024
	v_mfma_f32_16x16x32_bf16 v[80:83], v[216:219], v[160:163], v[80:83]
	v_addc_co_u32_e32 v113, vcc, 0, v113, vcc
	ds_read2_b64 v[216:219], v182 offset0:40 offset1:44
	s_waitcnt lgkmcnt(1)
	v_mfma_f32_16x16x32_bf16 v[24:27], v[178:181], v[156:159], v[24:27]
	v_add_co_u32_e32 v116, vcc, 0x300000, v116
	global_load_dwordx4 v[104:107], v[104:105], off
	v_mfma_f32_16x16x32_bf16 v[36:39], v[178:181], v[164:167], v[36:39]
	v_add_u32_e32 v182, 0xe000, v238
	v_addc_co_u32_e32 v117, vcc, 0, v117, vcc
	ds_read2_b64 v[178:181], v182 offset0:64 offset1:68
	s_waitcnt lgkmcnt(1)
	v_mfma_f32_16x16x32_bf16 v[24:27], v[216:219], v[152:155], v[24:27]
	global_load_dwordx4 v[112:115], v[112:113], off offset:1024
	v_pk_add_f32 v[210:211], v[192:193], v[210:211]
	global_load_dwordx4 v[116:119], v[116:117], off
	v_mfma_f32_16x16x32_bf16 v[36:39], v[216:219], v[160:163], v[36:39]
	v_pk_add_f32 v[176:177], v[176:177], v[210:211]
	ds_read2_b64 v[216:219], v182 offset0:72 offset1:76
	s_waitcnt lgkmcnt(1)
	v_mfma_f32_16x16x32_bf16 v[16:19], v[178:181], v[156:159], v[16:19]
	v_mfma_f32_16x16x32_bf16 v[32:35], v[178:181], v[164:167], v[32:35]
	v_add_u32_e32 v182, 0xe800, v238
	ds_read2_b64 v[178:181], v182 offset0:96 offset1:100
	s_waitcnt lgkmcnt(1)
	v_mfma_f32_16x16x32_bf16 v[16:19], v[216:219], v[152:155], v[16:19]
	v_mfma_f32_16x16x32_bf16 v[32:35], v[216:219], v[160:163], v[32:35]
	ds_read2_b64 v[216:219], v182 offset0:104 offset1:108
	s_waitcnt lgkmcnt(1)
	v_mfma_f32_16x16x32_bf16 v[28:31], v[178:181], v[156:159], v[28:31]
	v_mfma_f32_16x16x32_bf16 v[44:47], v[178:181], v[164:167], v[44:47]
	v_add_u32_e32 v182, 0xf000, v238
	ds_read2_b64 v[178:181], v182 offset0:128 offset1:132
	s_waitcnt lgkmcnt(1)
	v_mfma_f32_16x16x32_bf16 v[28:31], v[216:219], v[152:155], v[28:31]
	v_mfma_f32_16x16x32_bf16 v[44:47], v[216:219], v[160:163], v[44:47]
	ds_read2_b64 v[216:219], v182 offset0:136 offset1:140
	s_waitcnt lgkmcnt(1)
	v_mfma_f32_16x16x32_bf16 v[40:43], v[178:181], v[156:159], v[40:43]
	v_mfma_f32_16x16x32_bf16 v[52:55], v[178:181], v[164:167], v[52:55]
	v_add_u32_e32 v182, 0xf800, v238
	ds_read2_b64 v[178:181], v182 offset0:160 offset1:164
	s_waitcnt lgkmcnt(1)
	v_mfma_f32_16x16x32_bf16 v[40:43], v[216:219], v[152:155], v[40:43]
	v_mfma_f32_16x16x32_bf16 v[52:55], v[216:219], v[160:163], v[52:55]
	ds_read2_b64 v[216:219], v182 offset0:168 offset1:172
	s_waitcnt lgkmcnt(1)
	v_mfma_f32_16x16x32_bf16 v[12:15], v[178:181], v[156:159], v[12:15]
	v_mfma_f32_16x16x32_bf16 v[48:51], v[178:181], v[164:167], v[48:51]
	v_add_u32_e32 v182, 0xd000, v235
	ds_read2_b64 v[178:181], v182 offset1:4
	s_waitcnt lgkmcnt(1)
	v_mfma_f32_16x16x32_bf16 v[12:15], v[216:219], v[152:155], v[12:15]
	v_mfma_f32_16x16x32_bf16 v[48:51], v[216:219], v[160:163], v[48:51]
	ds_read2_b64 v[216:219], v182 offset0:8 offset1:12
	s_waitcnt lgkmcnt(1)
	v_mfma_f32_16x16x32_bf16 v[4:7], v[178:181], v[156:159], v[4:7]
	v_mfma_f32_16x16x32_bf16 v[8:11], v[178:181], v[164:167], v[8:11]
	v_add_u32_e32 v182, 0xd000, v236
	ds_read2_b64 v[178:181], v182 offset1:4
	s_waitcnt lgkmcnt(1)
	v_mfma_f32_16x16x32_bf16 v[4:7], v[216:219], v[152:155], v[4:7]
	v_mfma_f32_16x16x32_bf16 v[8:11], v[216:219], v[160:163], v[8:11]
	s_waitcnt lgkmcnt(0)
	v_mfma_f32_16x16x32_bf16 v[20:23], v[178:181], v[156:159], v[20:23]
	ds_read2_b64 v[156:159], v182 offset0:8 offset1:12
	v_mfma_f32_16x16x32_bf16 v[56:59], v[178:181], v[164:167], v[56:59]
	s_waitcnt lgkmcnt(0)
	v_mfma_f32_16x16x32_bf16 v[20:23], v[156:159], v[152:155], v[20:23]
	v_mfma_f32_16x16x32_bf16 v[56:59], v[156:159], v[160:163], v[56:59]

.LBB0_1016:
	s_add_i32 s6, s4, -1
	s_min_u32 s6, s6, s3
	s_mov_b32 s9, s7
	s_lshl_b32 s8, s6, 7
	v_lshl_add_u64 v[148:149], v[174:175], 0, s[8:9]
	s_mul_i32 s8, s6, 0x30000
	v_lshl_add_u64 v[144:145], v[172:173], 0, s[8:9]
	global_load_dwordx4 v[120:123], v[144:145], off offset:1024
	global_load_dwordx4 v[124:127], v[148:149], off
	ds_read_b128 v[152:155], v237
	ds_read_b128 v[156:159], v237 offset:64
	s_mov_b32 s6, 0xc000
	v_add_co_u32_e32 v128, vcc, s6, v144
	s_mov_b32 s6, 0xffff0000
	s_waitcnt lgkmcnt(1)
	v_mfma_f32_16x16x32_bf16 v[152:155], v[152:155], v[60:63], v[108:111]
	ds_read_b128 v[160:163], v237 offset:4416
	v_addc_co_u32_e32 v129, vcc, 0, v145, vcc
	s_waitcnt lgkmcnt(1)
	v_mfma_f32_16x16x32_bf16 v[152:155], v[156:159], v[64:67], v[152:155]
	ds_read_b128 v[156:159], v237 offset:4352
	v_add_co_u32_e32 v132, vcc, s10, v148
	global_load_dwordx4 v[128:131], v[128:129], off offset:1024
	s_nop 0
	v_addc_co_u32_e32 v133, vcc, 0, v149, vcc
	s_waitcnt lgkmcnt(0)
	v_mfma_f32_16x16x32_bf16 v[156:159], v[156:159], v[60:63], v[108:111]
	ds_read_b128 v[164:167], v237 offset:8768
	v_exp_f32_e32 v199, v155
	v_exp_f32_e32 v191, v153
	v_mfma_f32_16x16x32_bf16 v[156:159], v[160:163], v[64:67], v[156:159]
	ds_read_b128 v[160:163], v237 offset:8704
	v_add_co_u32_e32 v136, vcc, s11, v144
	s_waitcnt lgkmcnt(0)
	v_mfma_f32_16x16x32_bf16 v[160:163], v[160:163], v[60:63], v[108:111]
	s_nop 2
	s_nop 0
	v_exp_f32_e32 v197, v157
	v_exp_f32_e32 v189, v156
	v_mfma_f32_16x16x32_bf16 v[180:183], v[164:167], v[64:67], v[160:163]
	ds_read_b128 v[164:167], v237 offset:13120
	v_exp_f32_e32 v195, v158
	v_exp_f32_e32 v201, v159
	ds_read_b128 v[160:163], v237 offset:13056
	s_waitcnt lgkmcnt(0)
	v_mfma_f32_16x16x32_bf16 v[160:163], v[160:163], v[60:63], v[108:111]
	s_nop 1
	v_exp_f32_e32 v185, v183
	ds_read_b128 v[240:243], v237 offset:192
	v_exp_f32_e32 v181, v181
	v_mfma_f32_16x16x32_bf16 v[220:223], v[164:167], v[64:67], v[160:163]
	v_exp_f32_e32 v167, v154
	v_exp_f32_e32 v165, v152
	s_nop 0
	v_exp_f32_e32 v161, v180
	s_nop 2
	s_nop 0
	v_exp_f32_e32 v179, v220
	v_exp_f32_e32 v187, v221
	v_exp_f32_e32 v183, v222
	v_exp_f32_e32 v193, v223
	ds_read_b128 v[220:223], v237 offset:128
	s_waitcnt lgkmcnt(0)
	v_mfma_f32_16x16x32_bf16 v[220:223], v[220:223], v[68:71], v[108:111]
	ds_read_b128 v[244:247], v237 offset:4544
	ds_read_b128 v[224:227], v237 offset:8896
	v_mfma_f32_16x16x32_bf16 v[220:223], v[240:243], v[72:75], v[220:223]
	ds_read_b128 v[240:243], v237 offset:4480
	v_exp_f32_e32 v163, v182
	s_waitcnt lgkmcnt(0)
	v_mfma_f32_16x16x32_bf16 v[240:243], v[240:243], v[68:71], v[108:111]
	v_mfma_f32_16x16x32_bf16 v[240:243], v[244:247], v[72:75], v[240:243]
	ds_read_b128 v[244:247], v237 offset:8832
	v_cvt_pk_bf16_f32 v157, v167, v199
	s_waitcnt lgkmcnt(0)
	v_mfma_f32_16x16x32_bf16 v[244:247], v[244:247], v[68:71], v[108:111]
	v_mfma_f32_16x16x32_bf16 v[224:227], v[224:227], v[72:75], v[244:247]
	ds_read_b128 v[210:213], v237 offset:13248
	v_cvt_pk_bf16_f32 v156, v165, v191
	s_nop 0
	s_nop 3
	ds_read_b128 v[244:247], v237 offset:13184
	v_exp_f32_e32 v164, v220
	v_exp_f32_e32 v190, v221
	v_exp_f32_e32 v166, v222
	s_waitcnt lgkmcnt(0)
	v_mfma_f32_16x16x32_bf16 v[244:247], v[244:247], v[68:71], v[108:111]
	v_exp_f32_e32 v198, v223
	v_exp_f32_e32 v188, v240
	v_pk_add_f32 v[220:221], v[164:165], 0 op_sel_hi:[1,0]
	v_exp_f32_e32 v196, v241
	v_pk_add_f32 v[220:221], v[190:191], v[220:221]
	v_cvt_pk_bf16_f32 v159, v195, v201
	v_exp_f32_e32 v194, v242
	v_pk_add_f32 v[220:221], v[166:167], v[220:221]
	v_cvt_pk_bf16_f32 v158, v189, v197
	v_mfma_f32_16x16x32_bf16 v[210:213], v[210:213], v[72:75], v[244:247]
	v_add_f32_e64 v220, v198, v220
	v_add_f32_e64 v221, v199, v221
	v_exp_f32_e32 v200, v243
	v_cvt_pk_bf16_f32 v155, v183, v193
	v_cvt_pk_bf16_f32 v152, v161, v181
	v_pk_add_f32 v[220:221], v[220:221], v[188:189]
	v_exp_f32_e32 v160, v224
	v_cvt_pk_bf16_f32 v154, v179, v187
	v_cvt_pk_bf16_f32 v153, v163, v185
	v_pk_add_f32 v[220:221], v[196:197], v[220:221]
	v_exp_f32_e32 v180, v225
	v_pk_add_f32 v[220:221], v[194:195], v[220:221]
	v_exp_f32_e32 v162, v226
	v_exp_f32_e32 v184, v227
	v_exp_f32_e32 v178, v210
	v_exp_f32_e32 v186, v211
	v_pk_add_f32 v[210:211], v[200:201], v[220:221]
	v_exp_f32_e32 v182, v212
	v_pk_add_f32 v[210:211], v[210:211], v[160:161]
	v_pk_add_f32 v[210:211], v[180:181], v[210:211]
	v_pk_add_f32 v[210:211], v[162:163], v[210:211]
	v_bfe_u32 v165, v166, 16, 1
	v_pk_add_f32 v[210:211], v[184:185], v[210:211]
	v_pk_add_f32 v[210:211], v[210:211], v[178:179]
	v_exp_f32_e32 v192, v213
	v_pk_add_f32 v[210:211], v[186:187], v[210:211]
	v_bfe_u32 v163, v198, 16, 1
	v_add3_u32 v165, v166, v165, s33
	v_pk_add_f32 v[210:211], v[182:183], v[210:211]
	v_add3_u32 v163, v198, v163, s33
	v_lshrrev_b32_e32 v165, 16, v165
	v_and_or_b32 v165, v163, s6, v165
	v_cvt_pk_bf16_f32 v166, v188, v196
	v_bfe_u32 v163, v184, 16, 1
	v_add3_u32 v183, v184, v163, s33
	v_bfe_u32 v163, v162, 16, 1
	v_bfe_u32 v181, v182, 16, 1
	v_bfe_u32 v185, v178, 16, 1
	v_cvt_pk_bf16_f32 v167, v194, v200
	v_cvt_pk_bf16_f32 v164, v164, v190
	v_bfe_u32 v161, v192, 16, 1
	v_bfe_u32 v179, v186, 16, 1
	v_add3_u32 v181, v182, v181, s33
	v_add3_u32 v162, v162, v163, s33
	v_add3_u32 v163, v178, v185, s33
	v_add3_u32 v161, v192, v161, s33
	v_add3_u32 v179, v186, v179, s33
	v_lshrrev_b32_e32 v162, 16, v162
	v_lshrrev_b32_e32 v178, 16, v181
	v_lshrrev_b32_e32 v181, 16, v163
	v_add_u32_e32 v182, 0x4000, v238
	v_and_or_b32 v163, v161, s6, v178
	v_and_or_b32 v161, v183, s6, v162
	v_and_or_b32 v162, v179, s6, v181
	v_cvt_pk_bf16_f32 v160, v160, v180
	ds_read2_b64 v[178:181], v182 offset0:128 offset1:132
	ds_read2_b64 v[216:219], v182 offset0:136 offset1:140
	s_waitcnt lgkmcnt(1)
; DEVI void attn_prompt_item(const Params& p, int l, int bq, int h, int qc, char* smem) {
;     ...
;   __syncthreads();
;   AT_LOAD(RK0, RV0, 0);
;   AT_LOAD(RK1, RV1, 1);
;   AT_STORE(RK0, RV0, 0);
;   AT_LOAD(RK0, RV0, 2);
;   AT_STORE(RK1, RV1, 1);
;   lds_barrier();
;   for (int kt = 0; kt < nkt; kt += 2) {
;     AT_LOAD(RK1, RV1, kt + 3);
;     AT_COMPUTE(0);
;     lds_barrier();
;     AT_STORE(RK0, RV0, 0);
;     if (kt + 1 < nkt) {
;       AT_LOAD(RK0, RV0, kt + 4);
;       AT_COMPUTE(1);
;     }
;     lds_barrier();
;     AT_STORE(RK1, RV1, 1);
;   }
	v_mfma_f32_16x16x32_bf16 v[76:79], v[178:181], v[156:159], v[76:79]
	v_addc_co_u32_e32 v137, vcc, 0, v145, vcc
	v_add_co_u32_e32 v140, vcc, s12, v148
	v_mfma_f32_16x16x32_bf16 v[80:83], v[178:181], v[164:167], v[80:83]
	v_add_u32_e32 v182, 0x4800, v238
	v_addc_co_u32_e32 v141, vcc, 0, v149, vcc
	ds_read2_b64 v[178:181], v182 offset0:160 offset1:164
	s_waitcnt lgkmcnt(1)
	v_mfma_f32_16x16x32_bf16 v[76:79], v[216:219], v[152:155], v[76:79]
	v_add_co_u32_e32 v144, vcc, s13, v144
	global_load_dwordx4 v[132:135], v[132:133], off
	v_mfma_f32_16x16x32_bf16 v[80:83], v[216:219], v[160:163], v[80:83]
	v_addc_co_u32_e32 v145, vcc, 0, v145, vcc
	ds_read2_b64 v[216:219], v182 offset0:168 offset1:172
	s_waitcnt lgkmcnt(1)
	v_mfma_f32_16x16x32_bf16 v[24:27], v[178:181], v[156:159], v[24:27]
	v_add_co_u32_e32 v148, vcc, s14, v148
	global_load_dwordx4 v[136:139], v[136:137], off offset:1024
	v_mfma_f32_16x16x32_bf16 v[36:39], v[178:181], v[164:167], v[36:39]
	v_add_u32_e32 v182, 0x5000, v238
	v_addc_co_u32_e32 v149, vcc, 0, v149, vcc
	ds_read2_b64 v[178:181], v182 offset0:192 offset1:196
	s_waitcnt lgkmcnt(1)
	v_mfma_f32_16x16x32_bf16 v[24:27], v[216:219], v[152:155], v[24:27]
	global_load_dwordx4 v[140:143], v[140:141], off
	s_add_i32 s5, s4, -4
	global_load_dwordx4 v[144:147], v[144:145], off offset:1024
	v_mfma_f32_16x16x32_bf16 v[36:39], v[216:219], v[160:163], v[36:39]
	global_load_dwordx4 v[148:151], v[148:149], off
	v_pk_add_f32 v[210:211], v[192:193], v[210:211]
	ds_read2_b64 v[216:219], v182 offset0:200 offset1:204
	s_waitcnt lgkmcnt(1)
	v_mfma_f32_16x16x32_bf16 v[16:19], v[178:181], v[156:159], v[16:19]
	v_add_f32_e64 v176, v176, v210
	v_add_f32_e64 v177, v177, v211
	s_cmp_ge_u32 s5, s3
	v_mfma_f32_16x16x32_bf16 v[32:35], v[178:181], v[164:167], v[32:35]
	v_add_u32_e32 v182, 0x5800, v238
	ds_read2_b64 v[178:181], v182 offset0:224 offset1:228
	s_waitcnt lgkmcnt(1)
	v_mfma_f32_16x16x32_bf16 v[16:19], v[216:219], v[152:155], v[16:19]
	v_mfma_f32_16x16x32_bf16 v[32:35], v[216:219], v[160:163], v[32:35]
	ds_read2_b64 v[216:219], v182 offset0:232 offset1:236
	s_waitcnt lgkmcnt(1)
	v_mfma_f32_16x16x32_bf16 v[28:31], v[178:181], v[156:159], v[28:31]
	v_mfma_f32_16x16x32_bf16 v[44:47], v[178:181], v[164:167], v[44:47]
	v_add_u32_e32 v182, 0x6800, v238
	ds_read2_b64 v[178:181], v182 offset1:4
	s_waitcnt lgkmcnt(1)
	v_mfma_f32_16x16x32_bf16 v[28:31], v[216:219], v[152:155], v[28:31]
	v_mfma_f32_16x16x32_bf16 v[44:47], v[216:219], v[160:163], v[44:47]
	ds_read2_b64 v[216:219], v182 offset0:8 offset1:12
	s_waitcnt lgkmcnt(1)
	v_mfma_f32_16x16x32_bf16 v[40:43], v[178:181], v[156:159], v[40:43]
	v_mfma_f32_16x16x32_bf16 v[52:55], v[178:181], v[164:167], v[52:55]
	v_add_u32_e32 v182, 0x7000, v238
	ds_read2_b64 v[178:181], v182 offset0:32 offset1:36
	s_waitcnt lgkmcnt(1)
	v_mfma_f32_16x16x32_bf16 v[40:43], v[216:219], v[152:155], v[40:43]
	v_mfma_f32_16x16x32_bf16 v[52:55], v[216:219], v[160:163], v[52:55]
	ds_read2_b64 v[216:219], v182 offset0:40 offset1:44
	s_waitcnt lgkmcnt(1)
	v_mfma_f32_16x16x32_bf16 v[12:15], v[178:181], v[156:159], v[12:15]
	v_mfma_f32_16x16x32_bf16 v[48:51], v[178:181], v[164:167], v[48:51]
	v_add_u32_e32 v182, 0x7800, v238
	ds_read2_b64 v[178:181], v182 offset0:64 offset1:68
	s_waitcnt lgkmcnt(1)
	v_mfma_f32_16x16x32_bf16 v[12:15], v[216:219], v[152:155], v[12:15]
	v_mfma_f32_16x16x32_bf16 v[48:51], v[216:219], v[160:163], v[48:51]
	ds_read2_b64 v[216:219], v182 offset0:72 offset1:76
	s_waitcnt lgkmcnt(1)
	v_mfma_f32_16x16x32_bf16 v[4:7], v[178:181], v[156:159], v[4:7]
	v_mfma_f32_16x16x32_bf16 v[8:11], v[178:181], v[164:167], v[8:11]
	v_add_u32_e32 v182, 0x8000, v238
	ds_read2_b64 v[178:181], v182 offset0:96 offset1:100
	s_waitcnt lgkmcnt(1)
	v_mfma_f32_16x16x32_bf16 v[4:7], v[216:219], v[152:155], v[4:7]
	v_mfma_f32_16x16x32_bf16 v[8:11], v[216:219], v[160:163], v[8:11]
	s_waitcnt lgkmcnt(0)
	v_mfma_f32_16x16x32_bf16 v[20:23], v[178:181], v[156:159], v[20:23]
	ds_read2_b64 v[156:159], v182 offset0:104 offset1:108
	s_waitcnt lgkmcnt(0)
	s_barrier
	v_mfma_f32_16x16x32_bf16 v[56:59], v[178:181], v[164:167], v[56:59]
	s_waitcnt vmcnt(15)
	ds_write_b128 v232, v[84:87]
	s_waitcnt vmcnt(14)
	ds_write_b128 v233, v[88:91] offset:17408
	s_waitcnt vmcnt(13)
	ds_write_b128 v232, v[92:95] offset:4352
	s_waitcnt vmcnt(12)
	ds_write_b128 v233, v[96:99] offset:22016
	s_waitcnt vmcnt(11)
	ds_write_b128 v232, v[100:103] offset:8704
	s_waitcnt vmcnt(10)
	ds_write_b128 v233, v[104:107] offset:26624
	s_waitcnt vmcnt(9)
	ds_write_b128 v232, v[112:115] offset:13056
	s_waitcnt vmcnt(8)
	ds_write_b128 v233, v[116:119] offset:31232
	s_waitcnt lgkmcnt(8)
	v_mfma_f32_16x16x32_bf16 v[20:23], v[156:159], v[152:155], v[20:23]
	v_mfma_f32_16x16x32_bf16 v[56:59], v[156:159], v[160:163], v[56:59]
	s_cbranch_scc0 .LBB0_1014
	s_mov_b32 s7, s9
	s_branch .LBB0_1015
; DEVI void attn_prompt_item(const Params& p, int l, int bq, int h, int qc, char* smem) {
;     ...
;   {
;     int lsel = l;
;     asm volatile("" : "+s"(lsel));
;     const float lam_init = lsel == 0 ? 0.2f : 0.35550907f;
;     float lam;
;     {
;       const float* lp = p.in[12] + l * 256;
;       float a = lp[lane] * lp[64 + lane], b = lp[128 + lane] * lp[192 + lane];
;       a = wave_sum(a); b = wave_sum(b);
;       lam = expf(a) - expf(b) + lam_init;
;     }
;     float l0 = lrun[0], l1 = lrun[1];
;     l0 += __shfl_xor(l0, 16); l0 += __shfl_xor(l0, 32);
;     l1 += __shfl_xor(l1, 16); l1 += __shfl_xor(l1, 32);
;     const float i0 = 1.f / l0, i1 = lam / l1;
;     float ss = 0.f;
; #pragma unroll
;     for (int vt = 0; vt < 8; ++vt)
; #pragma unroll
;       for (int r = 0; r < 4; ++r) {
;         float v = o[0][vt][r] * i0 - o[1][vt][r] * i1;
;         o[0][vt][r] = v;
;         ss += v * v;
;       }
;     ss += __shfl_xor(ss, 16); ss += __shfl_xor(ss, 32);
.LBB0_1018:
	v_mov_b32_e32 v216, 0x300
	v_mov_b32_e32 v217, 0x1900
	v_mov_b32_e32 v218, 0x3fff
	v_mov_b32_e32 v219, 0x1170
	v_readlane_b32 s4, v254, 2
	s_mov_b32 s3, s4
	s_cmp_eq_u32 s3, 0
	s_cselect_b64 vcc, -1, 0
	v_mov_b32_e32 v60, 0x3eb60549
	v_mov_b32_e32 v61, 0x3e4ccccd
	v_cndmask_b32_e32 v60, v60, v61, vcc
	v_lshlrev_b32_e32 v61, 2, v231
	global_load_dword v62, v61, s[78:79]
	global_load_dword v63, v61, s[78:79] offset:256
	global_load_dword v65, v61, s[78:79] offset:512
	s_nop 0
	global_load_dword v61, v61, s[78:79] offset:768
	v_readlane_b32 s5, v254, 3
	v_sub_f32_e32 v69, 1.0, v60
	s_mov_b32 s69, s7
	s_waitcnt vmcnt(2)
	v_mul_f32_e32 v64, v62, v63
	s_nop 1
	v_mov_b32_dpp v64, v64 row_ror:8 row_mask:0xf bank_mask:0xf bound_ctrl:1
	v_fmac_f32_e32 v64, v62, v63
	s_waitcnt vmcnt(0)
	v_mul_f32_e32 v66, v65, v61
	v_add_f32_dpp v62, v64, v64 row_ror:4 row_mask:0xf bank_mask:0xf bound_ctrl:1
	s_nop 1
	v_add_f32_dpp v62, v62, v62 row_ror:2 row_mask:0xf bank_mask:0xf bound_ctrl:1
	s_nop 1
	v_add_f32_dpp v62, v62, v62 row_ror:1 row_mask:0xf bank_mask:0xf bound_ctrl:1
	s_nop 0
	v_readlane_b32 s3, v62, 16
	v_readlane_b32 s6, v62, 48
	v_readlane_b32 s4, v62, 0
	v_readlane_b32 s5, v62, 32
	v_mov_b32_e32 v62, s3
	v_mov_b32_e32 v63, s6
	v_pk_add_f32 v[62:63], s[4:5], v[62:63]
	s_nop 0
	v_add_f32_e32 v64, v62, v63
	v_mov_b32_dpp v62, v66 row_ror:8 row_mask:0xf bank_mask:0xf bound_ctrl:1
	v_fmac_f32_e32 v62, v65, v61
	s_nop 1
	v_add_f32_dpp v61, v62, v62 row_ror:4 row_mask:0xf bank_mask:0xf bound_ctrl:1
	s_nop 1
	v_add_f32_dpp v61, v61, v61 row_ror:2 row_mask:0xf bank_mask:0xf bound_ctrl:1
	s_nop 1
	v_add_f32_dpp v61, v61, v61 row_ror:1 row_mask:0xf bank_mask:0xf bound_ctrl:1
	s_nop 0
	v_readlane_b32 s3, v61, 16
	v_readlane_b32 s6, v61, 48
	v_readlane_b32 s4, v61, 0
	v_readlane_b32 s5, v61, 32
	v_mov_b32_e32 v62, s3
	v_mov_b32_e32 v63, s6
	v_pk_add_f32 v[62:63], s[4:5], v[62:63]
	s_mov_b32 s4, 0x3fb8aa3b
	v_add_f32_e32 v61, v62, v63
	v_mul_f32_e32 v62, 0x3fb8aa3b, v64
	v_fma_f32 v63, v64, s4, -v62
	v_rndne_f32_e32 v65, v62
	v_fmac_f32_e32 v63, 0x32a5705f, v64
	v_sub_f32_e32 v62, v62, v65
	v_add_f32_e32 v62, v62, v63
	v_exp_f32_e32 v62, v62
	v_cvt_i32_f32_e32 v63, v65
	s_mov_b32 s5, 0xc2ce8ed0
	v_cmp_ngt_f32_e32 vcc, s5, v64
	s_mov_b32 s3, 0x42b17218
	v_ldexp_f32 v62, v62, v63
	v_mul_f32_e32 v63, 0x3fb8aa3b, v61
	v_cndmask_b32_e32 v62, 0, v62, vcc
	v_cmp_nlt_f32_e32 vcc, s3, v64
	v_fma_f32 v64, v61, s4, -v63
	v_rndne_f32_e32 v65, v63
	v_fmac_f32_e32 v64, 0x32a5705f, v61
	v_sub_f32_e32 v63, v63, v65
	v_add_f32_e32 v63, v63, v64
	v_exp_f32_e32 v63, v63
	v_cvt_i32_f32_e32 v64, v65
	v_cndmask_b32_e32 v62, v204, v62, vcc
	v_cmp_ngt_f32_e32 vcc, s5, v61
	s_lshl_b32 s6, s2, 1
	v_ldexp_f32 v63, v63, v64
	v_cndmask_b32_e32 v63, 0, v63, vcc
	v_cmp_nlt_f32_e32 vcc, s3, v61
	s_mov_b64 s[2:3], 0
	s_nop 0
	v_cndmask_b32_e32 v61, v204, v63, vcc
	v_sub_f32_e32 v62, v62, v61
	ds_bpermute_b32 v61, v169, v177
	s_waitcnt lgkmcnt(0)
	v_add_f32_e32 v61, v177, v61
	ds_bpermute_b32 v63, v3, v61
	s_waitcnt lgkmcnt(0)
	v_add_f32_e32 v64, v61, v63
	ds_bpermute_b32 v61, v169, v176
	s_waitcnt lgkmcnt(0)
	v_add_f32_e32 v63, v176, v61
	ds_bpermute_b32 v61, v3, v63
	s_waitcnt lgkmcnt(0)
	v_pk_add_f32 v[62:63], v[60:61], v[62:63]
	v_div_scale_f32 v61, s[4:5], v64, v64, 1.0
	v_rcp_f32_e32 v65, v61
	s_nop 0
	v_fma_f32 v66, -v61, v65, 1.0
	v_fmac_f32_e32 v65, v66, v65
	v_div_scale_f32 v66, vcc, 1.0, v64, 1.0
	v_mul_f32_e32 v67, v66, v65
	v_fma_f32 v68, -v61, v67, v66
	v_fmac_f32_e32 v67, v68, v65
	v_fma_f32 v61, -v61, v67, v66
	v_div_fmas_f32 v61, v61, v65, v67
	v_div_fixup_f32 v66, v61, v64, 1.0
	v_div_scale_f32 v61, s[4:5], v63, v63, v62
	v_rcp_f32_e32 v64, v61
	v_readlane_b32 s4, v251, 56
	v_readlane_b32 s5, v251, 57
	v_fma_f32 v65, -v61, v64, 1.0
	v_fmac_f32_e32 v64, v65, v64
	v_div_scale_f32 v65, vcc, v62, v63, v62
	v_mul_f32_e32 v67, v65, v64
	v_fma_f32 v68, -v61, v67, v65
	v_fmac_f32_e32 v67, v68, v64
	v_fma_f32 v61, -v61, v67, v65
	v_div_fmas_f32 v61, v61, v64, v67
	v_div_fixup_f32 v68, v61, v63, v62
	v_lshlrev_b64 v[60:61], 12, v[170:171]
	v_lshl_add_u64 v[60:61], s[4:5], 0, v[60:61]
	v_lshl_add_u64 v[60:61], v[60:61], 0, s[6:7]
	v_lshlrev_b32_e32 v62, 3, v230
	v_mov_b32_e32 v63, v2
	v_lshl_add_u64 v[64:65], v[60:61], 0, v[62:63]
	v_mov_b32_e32 v62, v80
	v_mov_b32_e32 v63, v82
	v_lshlrev_b32_e32 v67, 4, v230
	v_mov_b32_e32 v60, v76
	v_mov_b32_e32 v61, v78
	v_pk_mul_f32 v[62:63], v[62:63], v[68:69] op_sel_hi:[1,0]
	v_mov_b32_e32 v82, v81
	v_pk_fma_f32 v[70:71], v[60:61], v[66:67], v[62:63] op_sel_hi:[1,0,1] neg_lo:[0,0,1] neg_hi:[0,0,1]
	v_mov_b32_e32 v78, v77
	v_pk_mul_f32 v[60:61], v[82:83], v[68:69] op_sel_hi:[1,0]
	v_pk_mul_f32 v[84:85], v[70:71], v[70:71]
	v_pk_fma_f32 v[72:73], v[78:79], v[66:67], v[60:61] op_sel_hi:[1,0,1] neg_lo:[0,0,1] neg_hi:[0,0,1]
	global_load_dwordx4 v[60:63], v67, s[82:83]
	v_mov_b32_e32 v79, v38
	v_mov_b32_e32 v38, v37
	v_mov_b32_e32 v78, v36
	v_pk_mul_f32 v[76:77], v[72:73], v[72:73]
	v_pk_mul_f32 v[78:79], v[78:79], v[68:69] op_sel_hi:[1,0]
	s_waitcnt vmcnt(0)
; DEVI void attn_prompt_item(const Params& p, int l, int bq, int h, int qc, char* smem) {
;     ...
;     float ss = 0.f;
; #pragma unroll
;     for (int vt = 0; vt < 8; ++vt)
; #pragma unroll
;       for (int r = 0; r < 4; ++r) {
;         float v = o[0][vt][r] * i0 - o[1][vt][r] * i1;
;         o[0][vt][r] = v;
;         ss += v * v;
;       }
;     ss += __shfl_xor(ss, 16); ss += __shfl_xor(ss, 32);
	v_mov_b32_e32 v74, v60
	v_mov_b32_e32 v75, v62
	v_mov_b32_e32 v62, v61
	v_mov_b32_e32 v60, v24
	v_mov_b32_e32 v61, v26
	v_mov_b32_e32 v26, v25
	v_pk_mul_f32 v[24:25], v[38:39], v[68:69] op_sel_hi:[1,0]
	v_pk_fma_f32 v[60:61], v[60:61], v[66:67], v[78:79] op_sel_hi:[1,0,1] neg_lo:[0,0,1] neg_hi:[0,0,1]
	v_pk_fma_f32 v[38:39], v[26:27], v[66:67], v[24:25] op_sel_hi:[1,0,1] neg_lo:[0,0,1] neg_hi:[0,0,1]
	v_mov_b32_e32 v27, v34
	v_mov_b32_e32 v34, v33
	v_mov_b32_e32 v24, v16
	v_mov_b32_e32 v25, v18
	v_mov_b32_e32 v18, v17
	v_pk_mul_f32 v[16:17], v[34:35], v[68:69] op_sel_hi:[1,0]
	v_mov_b32_e32 v26, v32
	v_pk_fma_f32 v[34:35], v[18:19], v[66:67], v[16:17] op_sel_hi:[1,0,1] neg_lo:[0,0,1] neg_hi:[0,0,1]
	v_mov_b32_e32 v18, v44
	v_mov_b32_e32 v19, v46
	v_mov_b32_e32 v16, v28
	v_mov_b32_e32 v17, v30
	v_pk_mul_f32 v[18:19], v[18:19], v[68:69] op_sel_hi:[1,0]
	v_mov_b32_e32 v46, v45
	v_pk_mul_f32 v[26:27], v[26:27], v[68:69] op_sel_hi:[1,0]
	v_pk_fma_f32 v[32:33], v[16:17], v[66:67], v[18:19] op_sel_hi:[1,0,1] neg_lo:[0,0,1] neg_hi:[0,0,1]
	v_mov_b32_e32 v30, v29
	v_pk_mul_f32 v[16:17], v[46:47], v[68:69] op_sel_hi:[1,0]
	v_mov_b32_e32 v18, v52
	v_mov_b32_e32 v19, v54
	v_pk_fma_f32 v[36:37], v[24:25], v[66:67], v[26:27] op_sel_hi:[1,0,1] neg_lo:[0,0,1] neg_hi:[0,0,1]
	v_pk_fma_f32 v[26:27], v[30:31], v[66:67], v[16:17] op_sel_hi:[1,0,1] neg_lo:[0,0,1] neg_hi:[0,0,1]
	v_mov_b32_e32 v16, v40
	v_mov_b32_e32 v17, v42
	v_pk_mul_f32 v[18:19], v[18:19], v[68:69] op_sel_hi:[1,0]
	v_mov_b32_e32 v54, v53
	v_pk_fma_f32 v[24:25], v[16:17], v[66:67], v[18:19] op_sel_hi:[1,0,1] neg_lo:[0,0,1] neg_hi:[0,0,1]
	v_mov_b32_e32 v42, v41
	v_pk_mul_f32 v[16:17], v[54:55], v[68:69] op_sel_hi:[1,0]
	v_pk_mul_f32 v[78:79], v[60:61], v[60:61]
	v_pk_fma_f32 v[18:19], v[42:43], v[66:67], v[16:17] op_sel_hi:[1,0,1] neg_lo:[0,0,1] neg_hi:[0,0,1]
	v_mov_b32_e32 v42, v48
	v_add_f32_e32 v48, v84, v76
	v_add_f32_e32 v48, v85, v48
	v_add_f32_e32 v48, v77, v48
	v_pk_mul_f32 v[80:81], v[38:39], v[38:39]
	v_add_f32_e32 v48, v78, v48
	v_add_f32_e32 v48, v80, v48
	v_add_f32_e32 v48, v79, v48
	v_pk_mul_f32 v[82:83], v[36:37], v[36:37]
	v_add_f32_e32 v48, v81, v48
	v_pk_mul_f32 v[86:87], v[34:35], v[34:35]
	v_add_f32_e32 v48, v82, v48
	v_add_f32_e32 v48, v86, v48
	v_add_f32_e32 v48, v83, v48
	v_pk_mul_f32 v[88:89], v[32:33], v[32:33]
	v_add_f32_e32 v48, v87, v48
	v_pk_mul_f32 v[28:29], v[26:27], v[26:27]
	v_add_f32_e32 v48, v88, v48
	v_add_f32_e32 v28, v28, v48
	v_add_f32_e32 v28, v89, v28
	v_pk_mul_f32 v[30:31], v[24:25], v[24:25]
	v_add_f32_e32 v28, v29, v28
	v_pk_mul_f32 v[40:41], v[18:19], v[18:19]
	v_mov_b32_e32 v43, v50
	v_add_f32_e32 v28, v30, v28
	v_mov_b32_e32 v16, v12
	v_mov_b32_e32 v17, v14
	v_pk_mul_f32 v[42:43], v[42:43], v[68:69] op_sel_hi:[1,0]
	v_mov_b32_e32 v50, v49
	v_add_f32_e32 v28, v40, v28
	v_pk_fma_f32 v[16:17], v[16:17], v[66:67], v[42:43] op_sel_hi:[1,0,1] neg_lo:[0,0,1] neg_hi:[0,0,1]
	v_mov_b32_e32 v14, v13
	v_pk_mul_f32 v[12:13], v[50:51], v[68:69] op_sel_hi:[1,0]
	v_mov_b32_e32 v46, v8
	v_mov_b32_e32 v47, v10
	v_mov_b32_e32 v10, v9
	v_add_f32_e32 v28, v31, v28
	v_pk_mul_f32 v[42:43], v[16:17], v[16:17]
	v_pk_fma_f32 v[14:15], v[14:15], v[66:67], v[12:13] op_sel_hi:[1,0,1] neg_lo:[0,0,1] neg_hi:[0,0,1]
	v_mov_b32_e32 v12, v4
	v_mov_b32_e32 v13, v6
	v_pk_mul_f32 v[46:47], v[46:47], v[68:69] op_sel_hi:[1,0]
	v_mov_b32_e32 v6, v5
	v_pk_mul_f32 v[4:5], v[10:11], v[68:69] op_sel_hi:[1,0]
	v_add_f32_e32 v28, v41, v28
	v_pk_mul_f32 v[44:45], v[14:15], v[14:15]
	v_pk_fma_f32 v[12:13], v[12:13], v[66:67], v[46:47] op_sel_hi:[1,0,1] neg_lo:[0,0,1] neg_hi:[0,0,1]
	v_pk_fma_f32 v[8:9], v[6:7], v[66:67], v[4:5] op_sel_hi:[1,0,1] neg_lo:[0,0,1] neg_hi:[0,0,1]
	v_add_f32_e32 v28, v42, v28
	v_mov_b32_e32 v4, v8
	v_mov_b32_e32 v5, v12
	v_add_f32_e32 v28, v44, v28
	v_pk_mul_f32 v[10:11], v[4:5], v[4:5]
	v_mov_b32_e32 v4, v9
	v_mov_b32_e32 v5, v13
	v_mov_b32_e32 v6, v56
	v_mov_b32_e32 v7, v58
	v_add_f32_e32 v28, v43, v28
	v_pk_mul_f32 v[46:47], v[4:5], v[4:5]
	v_mov_b32_e32 v4, v20
	v_mov_b32_e32 v5, v22
	v_pk_mul_f32 v[6:7], v[6:7], v[68:69] op_sel_hi:[1,0]
	v_mov_b32_e32 v58, v57
	v_add_f32_e32 v28, v45, v28
	v_pk_fma_f32 v[6:7], v[4:5], v[66:67], v[6:7] op_sel_hi:[1,0,1] neg_lo:[0,0,1] neg_hi:[0,0,1]
	v_mov_b32_e32 v22, v21
	v_pk_mul_f32 v[4:5], v[58:59], v[68:69] op_sel_hi:[1,0]
	v_add_f32_e32 v11, v11, v28
	v_pk_fma_f32 v[4:5], v[22:23], v[66:67], v[4:5] op_sel_hi:[1,0,1] neg_lo:[0,0,1] neg_hi:[0,0,1]
	v_add_f32_e32 v10, v10, v11
	v_mov_b32_e32 v20, v4
	v_mov_b32_e32 v21, v6
	v_add_f32_e32 v10, v47, v10
	v_pk_mul_f32 v[20:21], v[20:21], v[20:21]
	v_add_f32_e32 v10, v46, v10
	v_mov_b32_e32 v22, v5
	v_mov_b32_e32 v23, v7
	v_add_f32_e32 v10, v21, v10
	v_pk_mul_f32 v[22:23], v[22:23], v[22:23]
	v_add_f32_e32 v10, v20, v10
	v_add_f32_e32 v10, v23, v10
	v_add_f32_e32 v10, v22, v10
	ds_bpermute_b32 v11, v169, v10
	s_waitcnt lgkmcnt(0)
	v_add_f32_e32 v10, v10, v11
	ds_bpermute_b32 v3, v3, v10
	s_waitcnt lgkmcnt(0)
; DEVI u32 pack2(float a, float b) { return f2bf(a) | (f2bf(b) << 16); }
; DEVI void attn_prompt_item(const Params& p, int l, int bq, int h, int qc, char* smem) {
;     ...
;     ss += __shfl_xor(ss, 16); ss += __shfl_xor(ss, 32);
;     const float rstd = rsqrtf(ss * (1.f / 128.f) + 1e-6f) * (1.f - lam_init);
;     const float* sub = p.in[13] + l * 128;
; #pragma unroll
;     for (int vt = 0; vt < 8; ++vt) {
;       float4 g = *(const float4*)(sub + vt * 16 + quad * 4);
;       uint2 w = make_uint2(pack2(o[0][vt][0] * rstd * g.x, o[0][vt][1] * rstd * g.y), pack2(o[0][vt][2] * rstd * g.z, o[0][vt][3] * rstd * g.w));
;       *(uint2*)(cat + qrow * D + h * 128 + vt * 16 + quad * 4) = w;
;     }
	v_add_f32_e32 v3, v10, v3
	v_fmamk_f32 v3, v3, 0x3c000000, v0
	v_cmp_gt_f32_e32 vcc, s77, v3
	v_mul_f32_e32 v10, 0x4b800000, v3
	s_nop 0
	v_cndmask_b32_e32 v3, v3, v10, vcc
	v_rsq_f32_e32 v3, v3
	s_nop 0
	v_mul_f32_e32 v10, 0x45800000, v3
	v_cndmask_b32_e32 v3, v3, v10, vcc
	v_mul_f32_e32 v10, v69, v3
	v_pk_mul_f32 v[20:21], v[70:71], v[10:11] op_sel_hi:[1,0]
	v_pk_mul_f32 v[22:23], v[72:73], v[10:11] op_sel_hi:[1,0]
	v_pk_mul_f32 v[20:21], v[74:75], v[20:21]
	v_pk_mul_f32 v[22:23], v[62:63], v[22:23]
	v_and_b32_sdwa v3, v21, v202 dst_sel:DWORD dst_unused:UNUSED_PAD src0_sel:WORD_1 src1_sel:DWORD
	v_and_b32_sdwa v11, v20, v202 dst_sel:DWORD dst_unused:UNUSED_PAD src0_sel:WORD_1 src1_sel:DWORD
	v_add3_u32 v11, v20, v11, s33
	v_add3_u32 v3, v21, v3, s33
	v_and_b32_sdwa v20, v23, v202 dst_sel:DWORD dst_unused:UNUSED_PAD src0_sel:WORD_1 src1_sel:DWORD
	v_and_b32_sdwa v21, v22, v202 dst_sel:DWORD dst_unused:UNUSED_PAD src0_sel:WORD_1 src1_sel:DWORD
	v_add3_u32 v20, v23, v20, s33
	v_add3_u32 v21, v22, v21, s33
	v_and_b32_e32 v20, 0xffff0000, v20
	v_and_b32_e32 v22, 0xffff0000, v21
	v_or_b32_sdwa v21, v20, v3 dst_sel:DWORD dst_unused:UNUSED_PAD src0_sel:DWORD src1_sel:WORD_1
	v_or_b32_sdwa v20, v22, v11 dst_sel:DWORD dst_unused:UNUSED_PAD src0_sel:DWORD src1_sel:WORD_1
	global_store_dwordx2 v[64:65], v[20:21], off
	global_load_dwordx4 v[20:23], v67, s[82:83] offset:64
	v_pk_mul_f32 v[28:29], v[60:61], v[10:11] op_sel_hi:[1,0]
	s_waitcnt vmcnt(0)
	v_mov_b32_e32 v30, v20
	v_mov_b32_e32 v31, v22
	v_pk_mul_f32 v[28:29], v[30:31], v[28:29]
	v_pk_mul_f32 v[30:31], v[38:39], v[10:11] op_sel_hi:[1,0]
	v_mov_b32_e32 v22, v21
	v_pk_mul_f32 v[20:21], v[22:23], v[30:31]
	v_and_b32_sdwa v3, v29, v202 dst_sel:DWORD dst_unused:UNUSED_PAD src0_sel:WORD_1 src1_sel:DWORD
	v_and_b32_sdwa v22, v21, v202 dst_sel:DWORD dst_unused:UNUSED_PAD src0_sel:WORD_1 src1_sel:DWORD
	v_and_b32_sdwa v23, v20, v202 dst_sel:DWORD dst_unused:UNUSED_PAD src0_sel:WORD_1 src1_sel:DWORD
	v_and_b32_sdwa v11, v28, v202 dst_sel:DWORD dst_unused:UNUSED_PAD src0_sel:WORD_1 src1_sel:DWORD
	v_add3_u32 v21, v21, v22, s33
	v_add3_u32 v20, v20, v23, s33
	v_add3_u32 v11, v28, v11, s33
	v_add3_u32 v3, v29, v3, s33
	v_and_b32_e32 v21, 0xffff0000, v21
	v_and_b32_e32 v20, 0xffff0000, v20
	v_or_b32_sdwa v21, v21, v3 dst_sel:DWORD dst_unused:UNUSED_PAD src0_sel:DWORD src1_sel:WORD_1
	v_or_b32_sdwa v20, v20, v11 dst_sel:DWORD dst_unused:UNUSED_PAD src0_sel:DWORD src1_sel:WORD_1
	global_store_dwordx2 v[64:65], v[20:21], off offset:32
	global_load_dwordx4 v[20:23], v67, s[82:83] offset:128
	v_pk_mul_f32 v[28:29], v[36:37], v[10:11] op_sel_hi:[1,0]
	s_waitcnt vmcnt(0)
	v_mov_b32_e32 v30, v20
	v_mov_b32_e32 v31, v22
	v_pk_mul_f32 v[28:29], v[30:31], v[28:29]
	v_pk_mul_f32 v[30:31], v[34:35], v[10:11] op_sel_hi:[1,0]
	v_mov_b32_e32 v22, v21
	v_pk_mul_f32 v[20:21], v[22:23], v[30:31]
	v_and_b32_sdwa v3, v29, v202 dst_sel:DWORD dst_unused:UNUSED_PAD src0_sel:WORD_1 src1_sel:DWORD
	v_and_b32_sdwa v22, v21, v202 dst_sel:DWORD dst_unused:UNUSED_PAD src0_sel:WORD_1 src1_sel:DWORD
	v_and_b32_sdwa v23, v20, v202 dst_sel:DWORD dst_unused:UNUSED_PAD src0_sel:WORD_1 src1_sel:DWORD
	v_and_b32_sdwa v11, v28, v202 dst_sel:DWORD dst_unused:UNUSED_PAD src0_sel:WORD_1 src1_sel:DWORD
	v_add3_u32 v21, v21, v22, s33
	v_add3_u32 v20, v20, v23, s33
	v_add3_u32 v11, v28, v11, s33
	v_add3_u32 v3, v29, v3, s33
	v_and_b32_e32 v21, 0xffff0000, v21
	v_and_b32_e32 v20, 0xffff0000, v20
	v_or_b32_sdwa v21, v21, v3 dst_sel:DWORD dst_unused:UNUSED_PAD src0_sel:DWORD src1_sel:WORD_1
	v_or_b32_sdwa v20, v20, v11 dst_sel:DWORD dst_unused:UNUSED_PAD src0_sel:DWORD src1_sel:WORD_1
	global_store_dwordx2 v[64:65], v[20:21], off offset:64
	global_load_dwordx4 v[20:23], v67, s[82:83] offset:192
	v_pk_mul_f32 v[26:27], v[26:27], v[10:11] op_sel_hi:[1,0]
	v_pk_mul_f32 v[28:29], v[32:33], v[10:11] op_sel_hi:[1,0]
	s_waitcnt vmcnt(0)
	v_mov_b32_e32 v31, v22
	v_mov_b32_e32 v22, v21
	v_mov_b32_e32 v30, v20
	v_pk_mul_f32 v[20:21], v[22:23], v[26:27]
	v_pk_mul_f32 v[28:29], v[30:31], v[28:29]
	v_and_b32_sdwa v22, v21, v202 dst_sel:DWORD dst_unused:UNUSED_PAD src0_sel:WORD_1 src1_sel:DWORD
	v_and_b32_sdwa v23, v20, v202 dst_sel:DWORD dst_unused:UNUSED_PAD src0_sel:WORD_1 src1_sel:DWORD
	v_and_b32_sdwa v3, v29, v202 dst_sel:DWORD dst_unused:UNUSED_PAD src0_sel:WORD_1 src1_sel:DWORD
	v_and_b32_sdwa v11, v28, v202 dst_sel:DWORD dst_unused:UNUSED_PAD src0_sel:WORD_1 src1_sel:DWORD
	v_add3_u32 v21, v21, v22, s33
	v_add3_u32 v20, v20, v23, s33
	v_add3_u32 v11, v28, v11, s33
	v_add3_u32 v3, v29, v3, s33
	v_and_b32_e32 v21, 0xffff0000, v21
	v_and_b32_e32 v20, 0xffff0000, v20
	v_or_b32_sdwa v21, v21, v3 dst_sel:DWORD dst_unused:UNUSED_PAD src0_sel:DWORD src1_sel:WORD_1
	v_or_b32_sdwa v20, v20, v11 dst_sel:DWORD dst_unused:UNUSED_PAD src0_sel:DWORD src1_sel:WORD_1
	global_store_dwordx2 v[64:65], v[20:21], off offset:96
	global_load_dwordx4 v[20:23], v67, s[82:83] offset:256
	v_pk_mul_f32 v[18:19], v[18:19], v[10:11] op_sel_hi:[1,0]
	v_pk_mul_f32 v[24:25], v[24:25], v[10:11] op_sel_hi:[1,0]
	s_waitcnt vmcnt(0)
; DEVI u32 pack2(float a, float b) { return f2bf(a) | (f2bf(b) << 16); }
; DEVI void attn_prompt_item(const Params& p, int l, int bq, int h, int qc, char* smem) {
;     ...
; #pragma unroll
;     for (int vt = 0; vt < 8; ++vt) {
;       float4 g = *(const float4*)(sub + vt * 16 + quad * 4);
;       uint2 w = make_uint2(pack2(o[0][vt][0] * rstd * g.x, o[0][vt][1] * rstd * g.y), pack2(o[0][vt][2] * rstd * g.z, o[0][vt][3] * rstd * g.w));
;       *(uint2*)(cat + qrow * D + h * 128 + vt * 16 + quad * 4) = w;
;     }
	v_mov_b32_e32 v27, v22
	v_mov_b32_e32 v22, v21
	v_mov_b32_e32 v26, v20
	v_pk_mul_f32 v[18:19], v[22:23], v[18:19]
	v_pk_mul_f32 v[24:25], v[26:27], v[24:25]
	v_and_b32_sdwa v20, v19, v202 dst_sel:DWORD dst_unused:UNUSED_PAD src0_sel:WORD_1 src1_sel:DWORD
	v_and_b32_sdwa v21, v18, v202 dst_sel:DWORD dst_unused:UNUSED_PAD src0_sel:WORD_1 src1_sel:DWORD
	v_and_b32_sdwa v3, v25, v202 dst_sel:DWORD dst_unused:UNUSED_PAD src0_sel:WORD_1 src1_sel:DWORD
	v_and_b32_sdwa v11, v24, v202 dst_sel:DWORD dst_unused:UNUSED_PAD src0_sel:WORD_1 src1_sel:DWORD
	v_add3_u32 v19, v19, v20, s33
	v_add3_u32 v18, v18, v21, s33
	v_add3_u32 v11, v24, v11, s33
	v_add3_u32 v3, v25, v3, s33
	v_and_b32_e32 v19, 0xffff0000, v19
	v_and_b32_e32 v18, 0xffff0000, v18
	v_or_b32_sdwa v19, v19, v3 dst_sel:DWORD dst_unused:UNUSED_PAD src0_sel:DWORD src1_sel:WORD_1
	v_or_b32_sdwa v18, v18, v11 dst_sel:DWORD dst_unused:UNUSED_PAD src0_sel:DWORD src1_sel:WORD_1
	global_store_dwordx2 v[64:65], v[18:19], off offset:128
	global_load_dwordx4 v[18:21], v67, s[82:83] offset:320
	v_pk_mul_f32 v[16:17], v[16:17], v[10:11] op_sel_hi:[1,0]
	v_pk_mul_f32 v[14:15], v[14:15], v[10:11] op_sel_hi:[1,0]
	s_waitcnt vmcnt(0)
	v_mov_b32_e32 v22, v18
	v_mov_b32_e32 v23, v20
	v_pk_mul_f32 v[16:17], v[22:23], v[16:17]
	v_mov_b32_e32 v20, v19
	v_pk_mul_f32 v[14:15], v[20:21], v[14:15]
	v_and_b32_sdwa v3, v17, v202 dst_sel:DWORD dst_unused:UNUSED_PAD src0_sel:WORD_1 src1_sel:DWORD
	v_and_b32_sdwa v11, v16, v202 dst_sel:DWORD dst_unused:UNUSED_PAD src0_sel:WORD_1 src1_sel:DWORD
	v_add3_u32 v11, v16, v11, s33
	v_add3_u32 v3, v17, v3, s33
	v_and_b32_sdwa v16, v15, v202 dst_sel:DWORD dst_unused:UNUSED_PAD src0_sel:WORD_1 src1_sel:DWORD
	v_and_b32_sdwa v17, v14, v202 dst_sel:DWORD dst_unused:UNUSED_PAD src0_sel:WORD_1 src1_sel:DWORD
	v_add3_u32 v15, v15, v16, s33
	v_add3_u32 v14, v14, v17, s33
	v_and_b32_e32 v15, 0xffff0000, v15
	v_and_b32_e32 v14, 0xffff0000, v14
	v_or_b32_sdwa v15, v15, v3 dst_sel:DWORD dst_unused:UNUSED_PAD src0_sel:DWORD src1_sel:WORD_1
	v_or_b32_sdwa v14, v14, v11 dst_sel:DWORD dst_unused:UNUSED_PAD src0_sel:DWORD src1_sel:WORD_1
	global_store_dwordx2 v[64:65], v[14:15], off offset:160
	global_load_dwordx4 v[14:17], v67, s[82:83] offset:384
	v_pk_mul_f32 v[12:13], v[12:13], v[10:11] op_sel_hi:[1,0]
	v_pk_mul_f32 v[8:9], v[8:9], v[10:11] op_sel_hi:[1,0]
	s_waitcnt vmcnt(0)
	v_mov_b32_e32 v18, v14
	v_mov_b32_e32 v19, v16
	v_pk_mul_f32 v[12:13], v[18:19], v[12:13]
	v_mov_b32_e32 v16, v15
	v_pk_mul_f32 v[8:9], v[16:17], v[8:9]
	v_and_b32_sdwa v3, v13, v202 dst_sel:DWORD dst_unused:UNUSED_PAD src0_sel:WORD_1 src1_sel:DWORD
	v_and_b32_sdwa v11, v12, v202 dst_sel:DWORD dst_unused:UNUSED_PAD src0_sel:WORD_1 src1_sel:DWORD
	v_add3_u32 v11, v12, v11, s33
	v_add3_u32 v3, v13, v3, s33
	v_and_b32_sdwa v12, v9, v202 dst_sel:DWORD dst_unused:UNUSED_PAD src0_sel:WORD_1 src1_sel:DWORD
	v_and_b32_sdwa v13, v8, v202 dst_sel:DWORD dst_unused:UNUSED_PAD src0_sel:WORD_1 src1_sel:DWORD
	v_add3_u32 v9, v9, v12, s33
	v_add3_u32 v8, v8, v13, s33
	v_and_b32_e32 v9, 0xffff0000, v9
	v_and_b32_e32 v8, 0xffff0000, v8
	v_or_b32_sdwa v9, v9, v3 dst_sel:DWORD dst_unused:UNUSED_PAD src0_sel:DWORD src1_sel:WORD_1
	v_or_b32_sdwa v8, v8, v11 dst_sel:DWORD dst_unused:UNUSED_PAD src0_sel:DWORD src1_sel:WORD_1
	global_store_dwordx2 v[64:65], v[8:9], off offset:192
	global_load_dwordx4 v[12:15], v67, s[82:83] offset:448
	v_pk_mul_f32 v[6:7], v[6:7], v[10:11] op_sel_hi:[1,0]
	v_pk_mul_f32 v[4:5], v[4:5], v[10:11] op_sel_hi:[1,0]
	s_waitcnt vmcnt(0)
	v_mov_b32_e32 v8, v12
	v_mov_b32_e32 v9, v14
	v_pk_mul_f32 v[6:7], v[8:9], v[6:7]
	v_mov_b32_e32 v14, v13
	v_pk_mul_f32 v[4:5], v[14:15], v[4:5]
	v_and_b32_sdwa v3, v7, v202 dst_sel:DWORD dst_unused:UNUSED_PAD src0_sel:WORD_1 src1_sel:DWORD
	v_and_b32_sdwa v8, v6, v202 dst_sel:DWORD dst_unused:UNUSED_PAD src0_sel:WORD_1 src1_sel:DWORD
	v_add3_u32 v6, v6, v8, s33
	v_add3_u32 v3, v7, v3, s33
	v_and_b32_sdwa v7, v5, v202 dst_sel:DWORD dst_unused:UNUSED_PAD src0_sel:WORD_1 src1_sel:DWORD
	v_and_b32_sdwa v8, v4, v202 dst_sel:DWORD dst_unused:UNUSED_PAD src0_sel:WORD_1 src1_sel:DWORD
	v_add3_u32 v5, v5, v7, s33
	v_add3_u32 v4, v4, v8, s33
	v_and_b32_e32 v5, 0xffff0000, v5
	v_and_b32_e32 v4, 0xffff0000, v4
	v_or_b32_sdwa v5, v5, v3 dst_sel:DWORD dst_unused:UNUSED_PAD src0_sel:DWORD src1_sel:WORD_1
	v_or_b32_sdwa v4, v4, v6 dst_sel:DWORD dst_unused:UNUSED_PAD src0_sel:DWORD src1_sel:WORD_1
	global_store_dwordx2 v[64:65], v[4:5], off offset:224
